# poll back-off: s_sleep 2 between polls in the team and grid barrier spin loops
# baseline (speedup 1.0000x reference)
.Ltb_spin:
	s_sleep 2
	global_load_dword v4, v129, s[12:13] sc1
	s_waitcnt vmcnt(0)
	v_readfirstlane_b32 s20, v4
	s_cmp_ge_u32 s20, s19
	s_cbranch_scc1 .Ltb_done
	s_add_i32 s21, s21, 1
	s_cmp_lt_u32 s21, 0x2000
	s_cbranch_scc1 .Ltb_spin

.Lxb_spin:
	s_sleep 2
	global_load_dword v4, v129, s[12:13] sc1
	s_waitcnt vmcnt(0)
	v_readfirstlane_b32 s20, v4
	s_sub_i32 s20, s20, s19
	s_cmp_ge_i32 s20, 0
	s_cbranch_scc1 .Lxb_done
	s_add_i32 s21, s21, 1
	s_cmp_lt_u32 s21, 0x2000
	s_cbranch_scc1 .Lxb_spin
